# early L2 write-back by arriver 20 of each XCD
# speedup vs baseline: 1.0183x; 1.0183x over previous
.LBB0_140:
	s_or_b64 exec, exec, s[8:9]
	v_cvt_f32_u32_e32 v4, v2
	s_waitcnt vmcnt(0)
	v_readfirstlane_b32 s3, v3
	v_sub_u32_e32 v3, 0, v2
	v_rcp_iflag_f32_e32 v4, v4
	v_add_u32_e32 v5, s3, v1
	v_mul_f32_e32 v4, 0x4f7ffffe, v4
	v_cvt_u32_f32_e32 v4, v4
	v_mul_lo_u32 v1, v3, v4
	v_mul_hi_u32 v1, v4, v1
	v_add_u32_e32 v1, v4, v1
	v_mul_hi_u32 v1, v5, v1
	v_mul_lo_u32 v3, v1, v2
	v_sub_u32_e32 v3, v5, v3
	v_add_u32_e32 v4, 1, v1
	v_cmp_ge_u32_e32 vcc, v3, v2
	s_nop 1
	v_cndmask_b32_e32 v1, v1, v4, vcc
	v_sub_u32_e32 v4, v3, v2
	v_cndmask_b32_e32 v3, v3, v4, vcc
	v_add_u32_e32 v4, 1, v1
	v_cmp_ge_u32_e32 vcc, v3, v2
	v_add_u32_e32 v3, 1, v5
	s_nop 0
	v_cndmask_b32_e32 v1, v1, v4, vcc
	v_mul_lo_u32 v4, v2, v1
	v_add_u32_e32 v2, v4, v2
	v_cmp_ne_u32_e32 vcc, v3, v2
	s_and_saveexec_b64 s[6:7], vcc
	s_xor_b64 s[6:7], exec, s[6:7]
	s_cbranch_execz .LBB0_154
	s_waitcnt lgkmcnt(0)
	v_mov_b32_e32 v0, 0x2000
	buffer_inv sc1
	v_readfirstlane_b32 s12, v5
	s_and_b32 s12, s12, 31
	s_cmp_eq_u32 s12, 20
	s_cbranch_scc0 .Lewb_skip1

.LBB0_939:
	s_or_b64 exec, exec, s[16:17]
	v_cvt_f32_u32_e32 v4, v2
	s_waitcnt vmcnt(0)
	v_readfirstlane_b32 s2, v3
	v_sub_u32_e32 v3, 0, v2
	v_rcp_iflag_f32_e32 v4, v4
	v_add_u32_e32 v5, s2, v1
	v_mul_f32_e32 v4, 0x4f7ffffe, v4
	v_cvt_u32_f32_e32 v4, v4
	v_mul_lo_u32 v1, v3, v4
	v_mul_hi_u32 v1, v4, v1
	v_add_u32_e32 v1, v4, v1
	v_mul_hi_u32 v1, v5, v1
	v_mul_lo_u32 v3, v1, v2
	v_sub_u32_e32 v3, v5, v3
	v_add_u32_e32 v4, 1, v1
	v_cmp_ge_u32_e32 vcc, v3, v2
	s_nop 1
	v_cndmask_b32_e32 v1, v1, v4, vcc
	v_sub_u32_e32 v4, v3, v2
	v_cndmask_b32_e32 v3, v3, v4, vcc
	v_add_u32_e32 v4, 1, v1
	v_cmp_ge_u32_e32 vcc, v3, v2
	v_add_u32_e32 v3, 1, v5
	s_nop 0
	v_cndmask_b32_e32 v1, v1, v4, vcc
	v_mul_lo_u32 v4, v2, v1
	v_add_u32_e32 v2, v4, v2
	v_cmp_ne_u32_e32 vcc, v3, v2
	s_and_saveexec_b64 s[8:9], vcc
	s_xor_b64 s[14:15], exec, s[8:9]
	s_cbranch_execz .LBB0_953
	s_waitcnt lgkmcnt(0)
	buffer_inv sc1
	v_readfirstlane_b32 s18, v5
	s_and_b32 s18, s18, 31
	s_cmp_eq_u32 s18, 20
	s_cbranch_scc0 .Lewb_skip2

.LBB0_1593:
	s_or_b64 exec, exec, s[18:19]
	v_cvt_f32_u32_e32 v4, v2
	s_waitcnt vmcnt(0)
	v_readfirstlane_b32 s2, v3
	v_sub_u32_e32 v3, 0, v2
	v_rcp_iflag_f32_e32 v4, v4
	v_add_u32_e32 v5, s2, v1
	v_mul_f32_e32 v4, 0x4f7ffffe, v4
	v_cvt_u32_f32_e32 v4, v4
	v_mul_lo_u32 v1, v3, v4
	v_mul_hi_u32 v1, v4, v1
	v_add_u32_e32 v1, v4, v1
	v_mul_hi_u32 v1, v5, v1
	v_mul_lo_u32 v3, v1, v2
	v_sub_u32_e32 v3, v5, v3
	v_add_u32_e32 v4, 1, v1
	v_cmp_ge_u32_e32 vcc, v3, v2
	s_nop 1
	v_cndmask_b32_e32 v1, v1, v4, vcc
	v_sub_u32_e32 v4, v3, v2
	v_cndmask_b32_e32 v3, v3, v4, vcc
	v_add_u32_e32 v4, 1, v1
	v_cmp_ge_u32_e32 vcc, v3, v2
	v_add_u32_e32 v3, 1, v5
	s_nop 0
	v_cndmask_b32_e32 v1, v1, v4, vcc
	v_mul_lo_u32 v4, v2, v1
	v_add_u32_e32 v2, v4, v2
	v_cmp_ne_u32_e32 vcc, v3, v2
	s_and_saveexec_b64 s[8:9], vcc
	s_xor_b64 s[16:17], exec, s[8:9]
	s_cbranch_execz .LBB0_1607
	s_waitcnt lgkmcnt(0)
	buffer_inv sc1
	v_readfirstlane_b32 s20, v5
	s_and_b32 s20, s20, 31
	s_cmp_eq_u32 s20, 20
	s_cbranch_scc0 .Lewb_skip5

.LBB0_1713:
	s_or_b64 exec, exec, s[16:17]
	v_cvt_f32_u32_e32 v4, v2
	s_waitcnt vmcnt(0)
	v_readfirstlane_b32 s8, v3
	v_sub_u32_e32 v3, 0, v2
	v_rcp_iflag_f32_e32 v4, v4
	v_add_u32_e32 v5, s8, v1
	v_mul_f32_e32 v4, 0x4f7ffffe, v4
	v_cvt_u32_f32_e32 v4, v4
	v_mul_lo_u32 v1, v3, v4
	v_mul_hi_u32 v1, v4, v1
	v_add_u32_e32 v1, v4, v1
	v_mul_hi_u32 v1, v5, v1
	v_mul_lo_u32 v3, v1, v2
	v_sub_u32_e32 v3, v5, v3
	v_add_u32_e32 v4, 1, v1
	v_cmp_ge_u32_e32 vcc, v3, v2
	s_nop 1
	v_cndmask_b32_e32 v1, v1, v4, vcc
	v_sub_u32_e32 v4, v3, v2
	v_cndmask_b32_e32 v3, v3, v4, vcc
	v_add_u32_e32 v4, 1, v1
	v_cmp_ge_u32_e32 vcc, v3, v2
	v_add_u32_e32 v3, 1, v5
	s_nop 0
	v_cndmask_b32_e32 v1, v1, v4, vcc
	v_mul_lo_u32 v4, v2, v1
	v_add_u32_e32 v2, v4, v2
	v_cmp_ne_u32_e32 vcc, v3, v2
	s_and_saveexec_b64 s[8:9], vcc
	s_xor_b64 s[14:15], exec, s[8:9]
	s_cbranch_execz .LBB0_1727
	s_waitcnt lgkmcnt(0)
	buffer_inv sc1
	v_readfirstlane_b32 s18, v5
	s_and_b32 s18, s18, 31
	s_cmp_eq_u32 s18, 20
	s_cbranch_scc0 .Lewb_skip6
